# coalesce EpiUp bf16 stores via ds_bpermute (4 lanes = 64B contiguous)
# speedup vs baseline: 1.0175x; 1.0175x over previous
.LBB0_82:
	v_mbcnt_lo_u32_b32 v197, -1, 0
	v_mbcnt_hi_u32_b32 v197, -1, v197
	v_and_b32_e32 v198, 3, v197
	v_lshrrev_b32_e32 v197, 2, v197
	v_lshl_or_b32 v197, v198, 4, v197
	v_lshlrev_b32_e32 v196, 2, v197
	s_lshl_b32 s19, s4, 8
	s_add_i32 s19, s19, s43
	v_or_b32_e32 v151, s19, v5
	v_cmp_lt_i32_e32 vcc, s89, v151
	v_mov_b64_e32 v[146:147], 0
	s_nop 0
	v_cndmask_b32_e64 v142, v234, 7, vcc
	v_bitop3_b32 v142, v142, s19, v5 bitop3:0xe0
	v_cmp_lt_u32_e64 s[4:5], 5, v142
	s_and_b64 s[28:29], vcc, s[4:5]
	s_and_saveexec_b64 s[4:5], s[28:29]
	v_add_u32_e32 v143, 0xffffc000, v151
	v_lshrrev_b32_e32 v143, 2, v143
	v_and_b32_e32 v143, 0x3ffffff2, v143
	v_add3_u32 v144, v143, v142, -6
	v_mov_b64_e32 v[142:143], s[14:15]
	v_mad_u64_u32 v[146:147], s[28:29], v144, s90, v[142:143]
	s_or_b64 exec, exec, s[4:5]
	v_lshl_or_b32 v142, s26, 8, v149
	v_mov_b64_e32 v[144:145], s[10:11]
	v_mad_i64_i32 v[144:145], s[4:5], v151, s91, v[144:145]
	v_ashrrev_i32_e32 v143, 31, v142
	v_cmp_ne_u64_e32 vcc, 0, v[146:147]
	v_lshl_add_u64 v[144:145], v[142:143], 1, v[144:145]
	v_lshl_add_u64 v[146:147], v[142:143], 2, v[146:147]
	v_cvt_pk_bf16_f32 v152, v130, v131
	v_cvt_pk_bf16_f32 v153, v132, v133
	v_cvt_pk_bf16_f32 v154, v126, v127
	v_cvt_pk_bf16_f32 v155, v128, v129
	ds_bpermute_b32 v200, v196, v144
	ds_bpermute_b32 v201, v196, v145
	ds_bpermute_b32 v204, v196, v152
	ds_bpermute_b32 v205, v196, v153
	ds_bpermute_b32 v206, v196, v154
	ds_bpermute_b32 v207, v196, v155
	s_waitcnt lgkmcnt(0)
	global_store_dwordx4 v[200:201], v[204:207], off
	s_and_saveexec_b64 s[4:5], vcc
	s_cbranch_execz .LBB0_86
	global_store_dwordx4 v[146:147], v[130:133], off
	global_store_dwordx4 v[146:147], v[126:129], off offset:16
.LBB0_86:
	s_or_b64 exec, exec, s[4:5]
	s_nop 0
	v_cvt_pk_bf16_f32 v126, v122, v123
	v_cvt_pk_bf16_f32 v127, v124, v125
	v_cvt_pk_bf16_f32 v128, v118, v119
	v_cvt_pk_bf16_f32 v129, v120, v121
	ds_bpermute_b32 v208, v196, v126
	ds_bpermute_b32 v209, v196, v127
	ds_bpermute_b32 v210, v196, v128
	ds_bpermute_b32 v211, v196, v129
	s_waitcnt lgkmcnt(0)
	global_store_dwordx4 v[200:201], v[208:211], off offset:256
	s_and_saveexec_b64 s[4:5], vcc
	s_cbranch_execz .LBB0_88
	global_store_dwordx4 v[146:147], v[122:125], off offset:512
	global_store_dwordx4 v[146:147], v[118:121], off offset:528
.LBB0_88:
	s_or_b64 exec, exec, s[4:5]
	s_nop 0
	v_or_b32_e32 v118, 16, v151
	v_cmp_lt_i32_e32 vcc, s89, v118
	v_mov_b64_e32 v[120:121], 0
	s_nop 0
	v_cndmask_b32_e64 v119, v235, 7, vcc
	v_bitop3_b32 v119, v119, v151, 16 bitop3:0xe0
	v_cmp_lt_u32_e64 s[4:5], 5, v119
	s_and_b64 s[26:27], vcc, s[4:5]
	s_and_saveexec_b64 s[4:5], s[26:27]
	v_add_u32_e32 v120, 0xffffc010, v151
	v_lshrrev_b32_e32 v120, 2, v120
	v_and_b32_e32 v120, 0x3ffffff6, v120
	v_add3_u32 v119, v120, v119, -6
	v_mov_b64_e32 v[120:121], s[14:15]
	v_mad_u64_u32 v[120:121], s[26:27], v119, s90, v[120:121]
	s_or_b64 exec, exec, s[4:5]
	v_mov_b64_e32 v[122:123], s[10:11]
	v_mad_i64_i32 v[118:119], s[4:5], v118, s91, v[122:123]
	v_cmp_ne_u64_e32 vcc, 0, v[120:121]
	v_lshl_add_u64 v[118:119], v[142:143], 1, v[118:119]
	v_lshl_add_u64 v[120:121], v[142:143], 2, v[120:121]
	v_cvt_pk_bf16_f32 v122, v114, v115
	v_cvt_pk_bf16_f32 v123, v116, v117
	v_cvt_pk_bf16_f32 v124, v110, v111
	v_cvt_pk_bf16_f32 v125, v112, v113
	ds_bpermute_b32 v202, v196, v118
	ds_bpermute_b32 v203, v196, v119
	ds_bpermute_b32 v204, v196, v122
	ds_bpermute_b32 v205, v196, v123
	ds_bpermute_b32 v206, v196, v124
	ds_bpermute_b32 v207, v196, v125
	s_waitcnt lgkmcnt(0)
	global_store_dwordx4 v[202:203], v[204:207], off
	s_and_saveexec_b64 s[4:5], vcc
	s_cbranch_execz .LBB0_92
	global_store_dwordx4 v[120:121], v[114:117], off
	global_store_dwordx4 v[120:121], v[110:113], off offset:16
.LBB0_92:
	s_or_b64 exec, exec, s[4:5]
	s_nop 0
	v_cvt_pk_bf16_f32 v110, v106, v107
	v_cvt_pk_bf16_f32 v111, v108, v109
	v_cvt_pk_bf16_f32 v112, v102, v103
	v_cvt_pk_bf16_f32 v113, v104, v105
	ds_bpermute_b32 v208, v196, v110
	ds_bpermute_b32 v209, v196, v111
	ds_bpermute_b32 v210, v196, v112
	ds_bpermute_b32 v211, v196, v113
	s_waitcnt lgkmcnt(0)
	global_store_dwordx4 v[202:203], v[208:211], off offset:256
	s_and_saveexec_b64 s[4:5], vcc
	s_cbranch_execz .LBB0_94
	global_store_dwordx4 v[120:121], v[106:109], off offset:512
	global_store_dwordx4 v[120:121], v[102:105], off offset:528
.LBB0_94:
	s_or_b64 exec, exec, s[4:5]
	s_nop 0
	v_or_b32_e32 v102, 32, v151
	v_cmp_lt_i32_e32 vcc, s89, v102
	v_mov_b64_e32 v[104:105], 0
	s_nop 0
	v_cndmask_b32_e64 v103, v236, 7, vcc
	v_bitop3_b32 v103, v103, v151, 32 bitop3:0xe0
	v_cmp_lt_u32_e64 s[4:5], 5, v103
	s_and_b64 s[26:27], vcc, s[4:5]
	s_and_saveexec_b64 s[4:5], s[26:27]
	v_add_u32_e32 v104, 0xffffc020, v151
	v_lshrrev_b32_e32 v104, 2, v104
	v_and_b32_e32 v104, 0x3ffffffa, v104
	v_add3_u32 v103, v104, v103, -6
	v_mov_b64_e32 v[104:105], s[14:15]
	v_mad_u64_u32 v[104:105], s[26:27], v103, s90, v[104:105]
	s_or_b64 exec, exec, s[4:5]
	v_mov_b64_e32 v[106:107], s[10:11]
	v_mad_i64_i32 v[102:103], s[4:5], v102, s91, v[106:107]
	v_cmp_ne_u64_e32 vcc, 0, v[104:105]
	v_lshl_add_u64 v[102:103], v[142:143], 1, v[102:103]
	v_lshl_add_u64 v[104:105], v[142:143], 2, v[104:105]
	v_cvt_pk_bf16_f32 v106, v98, v99
	v_cvt_pk_bf16_f32 v107, v100, v101
	v_cvt_pk_bf16_f32 v108, v94, v95
	v_cvt_pk_bf16_f32 v109, v96, v97
	ds_bpermute_b32 v200, v196, v102
	ds_bpermute_b32 v201, v196, v103
	ds_bpermute_b32 v204, v196, v106
	ds_bpermute_b32 v205, v196, v107
	ds_bpermute_b32 v206, v196, v108
	ds_bpermute_b32 v207, v196, v109
	s_waitcnt lgkmcnt(0)
	global_store_dwordx4 v[200:201], v[204:207], off
	s_and_saveexec_b64 s[4:5], vcc
	s_cbranch_execz .LBB0_98
	global_store_dwordx4 v[104:105], v[98:101], off
	global_store_dwordx4 v[104:105], v[94:97], off offset:16
.LBB0_98:
	s_or_b64 exec, exec, s[4:5]
	s_nop 0
	v_cvt_pk_bf16_f32 v94, v90, v91
	v_cvt_pk_bf16_f32 v95, v92, v93
	v_cvt_pk_bf16_f32 v96, v86, v87
	v_cvt_pk_bf16_f32 v97, v88, v89
	ds_bpermute_b32 v208, v196, v94
	ds_bpermute_b32 v209, v196, v95
	ds_bpermute_b32 v210, v196, v96
	ds_bpermute_b32 v211, v196, v97
	s_waitcnt lgkmcnt(0)
	global_store_dwordx4 v[200:201], v[208:211], off offset:256
	s_and_saveexec_b64 s[4:5], vcc
	s_cbranch_execz .LBB0_100
	global_store_dwordx4 v[104:105], v[90:93], off offset:512
	global_store_dwordx4 v[104:105], v[86:89], off offset:528

.LBB0_108:
	s_or_b64 exec, exec, s[4:5]
	v_mov_b64_e32 v[90:91], s[10:11]
	v_mad_i64_i32 v[88:89], s[4:5], v88, s91, v[90:91]
	v_cmp_ne_u64_e32 vcc, 0, v[86:87]
	v_lshl_add_u64 v[88:89], v[142:143], 1, v[88:89]
	v_lshl_add_u64 v[86:87], v[142:143], 2, v[86:87]
	v_cvt_pk_bf16_f32 v90, v82, v83
	v_cvt_pk_bf16_f32 v91, v84, v85
	v_cvt_pk_bf16_f32 v92, v78, v79
	v_cvt_pk_bf16_f32 v93, v80, v81
	ds_bpermute_b32 v202, v196, v88
	ds_bpermute_b32 v203, v196, v89
	ds_bpermute_b32 v204, v196, v90
	ds_bpermute_b32 v205, v196, v91
	ds_bpermute_b32 v206, v196, v92
	ds_bpermute_b32 v207, v196, v93
	s_waitcnt lgkmcnt(0)
	global_store_dwordx4 v[202:203], v[204:207], off
	s_and_saveexec_b64 s[4:5], vcc
	s_cbranch_execz .LBB0_110
	global_store_dwordx4 v[86:87], v[82:85], off
	global_store_dwordx4 v[86:87], v[78:81], off offset:16
.LBB0_110:
	s_or_b64 exec, exec, s[4:5]
	s_nop 0
	v_cvt_pk_bf16_f32 v78, v74, v75
	v_cvt_pk_bf16_f32 v79, v76, v77
	v_cvt_pk_bf16_f32 v80, v70, v71
	v_cvt_pk_bf16_f32 v81, v72, v73
	ds_bpermute_b32 v208, v196, v78
	ds_bpermute_b32 v209, v196, v79
	ds_bpermute_b32 v210, v196, v80
	ds_bpermute_b32 v211, v196, v81
	s_waitcnt lgkmcnt(0)
	global_store_dwordx4 v[202:203], v[208:211], off offset:256
	s_and_saveexec_b64 s[4:5], vcc
	s_cbranch_execz .LBB0_112
	global_store_dwordx4 v[86:87], v[74:77], off offset:512
	global_store_dwordx4 v[86:87], v[70:73], off offset:528
.LBB0_112:
	s_or_b64 exec, exec, s[4:5]
	v_cmp_lt_i32_e32 vcc, s92, v151
	v_add_u32_e32 v74, 0x80, v151
	v_mov_b64_e32 v[72:73], 0
	v_cndmask_b32_e64 v70, v234, 7, vcc
	v_and_b32_e32 v70, v70, v74
	v_cmp_lt_u32_e64 s[4:5], 5, v70
	s_and_b64 s[26:27], vcc, s[4:5]
	s_and_saveexec_b64 s[4:5], s[26:27]
	v_add_u32_e32 v71, 0xffffc080, v151
	v_lshrrev_b32_e32 v71, 2, v71
	v_and_b32_e32 v71, 0x3ffffff2, v71
	v_add3_u32 v72, v71, v70, -6
	v_mov_b64_e32 v[70:71], s[14:15]
	v_mad_u64_u32 v[72:73], s[26:27], v72, s90, v[70:71]
	s_or_b64 exec, exec, s[4:5]
	v_mov_b64_e32 v[70:71], s[10:11]
	v_mad_i64_i32 v[70:71], s[4:5], v74, s91, v[70:71]
	v_cmp_ne_u64_e32 vcc, 0, v[72:73]
	v_lshl_add_u64 v[70:71], v[142:143], 1, v[70:71]
	v_lshl_add_u64 v[72:73], v[142:143], 2, v[72:73]
	v_cvt_pk_bf16_f32 v76, v66, v67
	v_cvt_pk_bf16_f32 v77, v68, v69
	v_cvt_pk_bf16_f32 v78, v62, v63
	v_cvt_pk_bf16_f32 v79, v64, v65
	ds_bpermute_b32 v200, v196, v70
	ds_bpermute_b32 v201, v196, v71
	ds_bpermute_b32 v204, v196, v76
	ds_bpermute_b32 v205, v196, v77
	ds_bpermute_b32 v206, v196, v78
	ds_bpermute_b32 v207, v196, v79
	s_waitcnt lgkmcnt(0)
	global_store_dwordx4 v[200:201], v[204:207], off
	s_and_saveexec_b64 s[4:5], vcc
	s_cbranch_execz .LBB0_116
	global_store_dwordx4 v[72:73], v[66:69], off
	global_store_dwordx4 v[72:73], v[62:65], off offset:16
.LBB0_116:
	s_or_b64 exec, exec, s[4:5]
	s_nop 0
	v_cvt_pk_bf16_f32 v62, v58, v59
	v_cvt_pk_bf16_f32 v63, v60, v61
	v_cvt_pk_bf16_f32 v64, v54, v55
	v_cvt_pk_bf16_f32 v65, v56, v57
	ds_bpermute_b32 v208, v196, v62
	ds_bpermute_b32 v209, v196, v63
	ds_bpermute_b32 v210, v196, v64
	ds_bpermute_b32 v211, v196, v65
	s_waitcnt lgkmcnt(0)
	global_store_dwordx4 v[200:201], v[208:211], off offset:256
	s_and_saveexec_b64 s[4:5], vcc
	s_cbranch_execz .LBB0_118
	global_store_dwordx4 v[72:73], v[58:61], off offset:512
	global_store_dwordx4 v[72:73], v[54:57], off offset:528
.LBB0_118:
	s_or_b64 exec, exec, s[4:5]
	s_movk_i32 s4, 0x3f6f
	v_cmp_lt_i32_e32 vcc, s4, v151
	v_add_u32_e32 v54, 0x90, v151
	v_mov_b64_e32 v[56:57], 0
	v_cndmask_b32_e64 v55, v235, 7, vcc
	v_and_b32_e32 v55, v55, v54
	v_cmp_lt_u32_e64 s[4:5], 5, v55
	s_and_b64 s[26:27], vcc, s[4:5]
	s_and_saveexec_b64 s[4:5], s[26:27]
	v_add_u32_e32 v56, 0xffffc090, v151
	v_lshrrev_b32_e32 v56, 2, v56
	v_and_b32_e32 v56, 0x3ffffff6, v56
	v_add3_u32 v55, v56, v55, -6
	v_mov_b64_e32 v[56:57], s[14:15]
	v_mad_u64_u32 v[56:57], s[26:27], v55, s90, v[56:57]
	s_or_b64 exec, exec, s[4:5]
	v_mov_b64_e32 v[58:59], s[10:11]
	v_mad_i64_i32 v[54:55], s[4:5], v54, s91, v[58:59]
	v_cmp_ne_u64_e32 vcc, 0, v[56:57]
	v_lshl_add_u64 v[54:55], v[142:143], 1, v[54:55]
	v_lshl_add_u64 v[56:57], v[142:143], 2, v[56:57]
	v_cvt_pk_bf16_f32 v58, v50, v51
	v_cvt_pk_bf16_f32 v59, v52, v53
	v_cvt_pk_bf16_f32 v60, v46, v47
	v_cvt_pk_bf16_f32 v61, v48, v49
	ds_bpermute_b32 v202, v196, v54
	ds_bpermute_b32 v203, v196, v55
	ds_bpermute_b32 v204, v196, v58
	ds_bpermute_b32 v205, v196, v59
	ds_bpermute_b32 v206, v196, v60
	ds_bpermute_b32 v207, v196, v61
	s_waitcnt lgkmcnt(0)
	global_store_dwordx4 v[202:203], v[204:207], off
	s_and_saveexec_b64 s[4:5], vcc
	s_cbranch_execz .LBB0_122
	global_store_dwordx4 v[56:57], v[50:53], off
	global_store_dwordx4 v[56:57], v[46:49], off offset:16
.LBB0_122:
	s_or_b64 exec, exec, s[4:5]
	s_nop 0
	v_cvt_pk_bf16_f32 v46, v42, v43
	v_cvt_pk_bf16_f32 v47, v44, v45
	v_cvt_pk_bf16_f32 v48, v38, v39
	v_cvt_pk_bf16_f32 v49, v40, v41
	ds_bpermute_b32 v208, v196, v46
	ds_bpermute_b32 v209, v196, v47
	ds_bpermute_b32 v210, v196, v48
	ds_bpermute_b32 v211, v196, v49
	s_waitcnt lgkmcnt(0)
	global_store_dwordx4 v[202:203], v[208:211], off offset:256
	s_and_saveexec_b64 s[4:5], vcc
	s_cbranch_execz .LBB0_124
	global_store_dwordx4 v[56:57], v[42:45], off offset:512
	global_store_dwordx4 v[56:57], v[38:41], off offset:528
.LBB0_124:
	s_or_b64 exec, exec, s[4:5]
	v_cmp_lt_i32_e32 vcc, s93, v151
	v_add_u32_e32 v38, 0xa0, v151
	v_mov_b64_e32 v[40:41], 0
	v_cndmask_b32_e64 v39, v236, 7, vcc
	v_and_b32_e32 v39, v39, v38
	v_cmp_lt_u32_e64 s[4:5], 5, v39
	s_and_b64 s[26:27], vcc, s[4:5]
	s_and_saveexec_b64 s[4:5], s[26:27]
	v_add_u32_e32 v40, 0xffffc0a0, v151
	v_lshrrev_b32_e32 v40, 2, v40
	v_and_b32_e32 v40, 0x3ffffffa, v40
	v_add3_u32 v39, v40, v39, -6
	v_mov_b64_e32 v[40:41], s[14:15]
	v_mad_u64_u32 v[40:41], s[26:27], v39, s90, v[40:41]
	s_or_b64 exec, exec, s[4:5]
	v_mov_b64_e32 v[42:43], s[10:11]
	v_mad_i64_i32 v[38:39], s[4:5], v38, s91, v[42:43]
	v_cmp_ne_u64_e32 vcc, 0, v[40:41]
	v_lshl_add_u64 v[38:39], v[142:143], 1, v[38:39]
	v_lshl_add_u64 v[40:41], v[142:143], 2, v[40:41]
	v_cvt_pk_bf16_f32 v42, v34, v35
	v_cvt_pk_bf16_f32 v43, v36, v37
	v_cvt_pk_bf16_f32 v44, v30, v31
	v_cvt_pk_bf16_f32 v45, v32, v33
	ds_bpermute_b32 v200, v196, v38
	ds_bpermute_b32 v201, v196, v39
	ds_bpermute_b32 v204, v196, v42
	ds_bpermute_b32 v205, v196, v43
	ds_bpermute_b32 v206, v196, v44
	ds_bpermute_b32 v207, v196, v45
	s_waitcnt lgkmcnt(0)
	global_store_dwordx4 v[200:201], v[204:207], off
	s_and_saveexec_b64 s[4:5], vcc
	s_cbranch_execz .LBB0_128
	global_store_dwordx4 v[40:41], v[34:37], off
	global_store_dwordx4 v[40:41], v[30:33], off offset:16
.LBB0_128:
	s_or_b64 exec, exec, s[4:5]
	s_nop 0
	v_cvt_pk_bf16_f32 v30, v26, v27
	v_cvt_pk_bf16_f32 v31, v28, v29
	v_cvt_pk_bf16_f32 v32, v22, v23
	v_cvt_pk_bf16_f32 v33, v24, v25
	ds_bpermute_b32 v208, v196, v30
	ds_bpermute_b32 v209, v196, v31
	ds_bpermute_b32 v210, v196, v32
	ds_bpermute_b32 v211, v196, v33
	s_waitcnt lgkmcnt(0)
	global_store_dwordx4 v[200:201], v[208:211], off offset:256
	s_and_saveexec_b64 s[4:5], vcc
	s_cbranch_execz .LBB0_130
	global_store_dwordx4 v[40:41], v[26:29], off offset:512
	global_store_dwordx4 v[40:41], v[22:25], off offset:528

.LBB0_138:
	s_or_b64 exec, exec, s[4:5]
	v_mov_b64_e32 v[26:27], s[10:11]
	v_mad_i64_i32 v[24:25], s[4:5], v24, s91, v[26:27]
	v_cmp_ne_u64_e32 vcc, 0, v[22:23]
	v_lshl_add_u64 v[24:25], v[142:143], 1, v[24:25]
	v_lshl_add_u64 v[22:23], v[142:143], 2, v[22:23]
	v_cvt_pk_bf16_f32 v26, v18, v19
	v_cvt_pk_bf16_f32 v27, v20, v21
	v_cvt_pk_bf16_f32 v28, v14, v15
	v_cvt_pk_bf16_f32 v29, v16, v17
	ds_bpermute_b32 v202, v196, v24
	ds_bpermute_b32 v203, v196, v25
	ds_bpermute_b32 v204, v196, v26
	ds_bpermute_b32 v205, v196, v27
	ds_bpermute_b32 v206, v196, v28
	ds_bpermute_b32 v207, v196, v29
	s_waitcnt lgkmcnt(0)
	global_store_dwordx4 v[202:203], v[204:207], off
	s_and_saveexec_b64 s[4:5], vcc
	s_cbranch_execz .LBB0_140
	global_store_dwordx4 v[22:23], v[18:21], off
	global_store_dwordx4 v[22:23], v[14:17], off offset:16
.LBB0_140:
	s_or_b64 exec, exec, s[4:5]
	s_nop 0
	v_cvt_pk_bf16_f32 v14, v10, v11
	v_cvt_pk_bf16_f32 v15, v12, v13
	v_cvt_pk_bf16_f32 v16, v6, v7
	v_cvt_pk_bf16_f32 v17, v8, v9
	ds_bpermute_b32 v208, v196, v14
	ds_bpermute_b32 v209, v196, v15
	ds_bpermute_b32 v210, v196, v16
	ds_bpermute_b32 v211, v196, v17
	s_waitcnt lgkmcnt(0)
	global_store_dwordx4 v[202:203], v[208:211], off offset:256
	s_and_saveexec_b64 s[4:5], vcc
	s_cbranch_execz .LBB0_142
	global_store_dwordx4 v[22:23], v[10:13], off offset:512
	global_store_dwordx4 v[22:23], v[6:9], off offset:528
